# P11 combine: g2 loads hoisted to row start, wait-free row tail (4 back-to-back stores); barrier poll s_sleep 8
# speedup vs baseline: 1.0142x; 1.0019x over previous
; __global__ void __launch_bounds__(NTH, 2) mega_kernel(Params p) {
;     ...
;   phase0a(p, smem);
;   wait_mod(p);
;   phase1(p);
;   phase0b(p, smem);
;   grid.sync();
.Lgs1_poll:
	global_load_dword v2, v0, s[6:7] offset:128 sc1
	s_waitcnt vmcnt(0)
	v_cmp_gt_u32_e32 vcc, s8, v2
	s_cbranch_vccz .Lgs1_done
	s_sleep 8
	s_branch .Lgs1_poll

; DI float bf_lo(unsigned u) { return __uint_as_float(u << 16); }
; DI float bf_hi(unsigned u) { return __uint_as_float(u & 0xffff0000u); }
; DI void phase11(const Params& p) {
;     ...
;   for (int R = gw; R < NT; R += nw) {
;     const int b = R >> 11;
;     const int myslot = nslot;
;     uint2 xu[4];
; #pragma unroll
;     for (int i = 0; i < 4; ++i) xu[i] = nx[i];
;     {
;       const int Rn = R + nw;
;       nslot = slotOf(Rn);
;       const bf16_t* xs = p.x1b + (size_t)(Rn < NT ? Rn : 0) * DM + lane * 4;
; #pragma unroll
;       for (int i = 0; i < 4; ++i) nx[i] = *(const uint2*)(xs + 256 * i);
;     }
;     unsigned long long mask = __ballot(myslot >= 0);
;     float4 a[4];
; #pragma unroll
;     for (int i = 0; i < 4; ++i) a[i] = make_float4(0.f, 0.f, 0.f, 0.f);
;     while (mask) {
;       const int e = __ffsll((long long)mask) - 1; mask &= mask - 1ull;
;       const int slot = __shfl(myslot, e);
;       const float g = p.gate[(b * NE + e) * CAP + slot];
;       const bf16_t* y = p.Y + ((size_t)(b * NE + e) * CAP + slot) * DM + lane * 4;
; #pragma unroll
;       for (int i = 0; i < 4; ++i) {
;         const uint2 u = *(const uint2*)(y + 256 * i);
;         a[i].x += g * bf_lo(u.x); a[i].y += g * bf_hi(u.x); a[i].z += g * bf_lo(u.y); a[i].w += g * bf_hi(u.y);
;       }
;     }
;     const float* g2 = p.mod + b * 6144 + 5120;
;     float* o = p.out + (size_t)R * DM;
; #pragma unroll
;     for (int i = 0; i < 4; ++i) {
;       const int d = lane * 4 + 256 * i;
;       const float4 gv = *(const float4*)(g2 + d);
;       *(float4*)(o + d) = make_float4(bf_lo(xu[i].x) + gv.x * a[i].x, bf_hi(xu[i].x) + gv.y * a[i].y, bf_lo(xu[i].y) + gv.z * a[i].z, bf_hi(xu[i].y) + gv.w * a[i].w);
;     }
.LBB0_1387:
	v_ashrrev_i32_e32 v21, 31, v20
	v_lshlrev_b64 v[20:21], 12, v[20:21]
	v_lshl_add_u64 v[62:63], v[6:7], 0, v[20:21]
	s_and_b64 s[0:1], exec, s[0:1]
	s_or_b64 s[10:11], s[0:1], s[10:11]
	s_waitcnt vmcnt(4)
	v_lshlrev_b32_e32 v96, 16, v24
	v_and_b32_e32 v97, 0xffff0000, v24
	v_lshlrev_b32_e32 v98, 16, v25
	v_and_b32_e32 v99, 0xffff0000, v25
	v_lshlrev_b32_e32 v100, 16, v22
	v_and_b32_e32 v101, 0xffff0000, v22
	v_lshlrev_b32_e32 v102, 16, v23
	v_and_b32_e32 v103, 0xffff0000, v23
	v_lshlrev_b32_e32 v104, 16, v18
	v_and_b32_e32 v105, 0xffff0000, v18
	v_lshlrev_b32_e32 v106, 16, v19
	v_and_b32_e32 v107, 0xffff0000, v19
	v_lshlrev_b32_e32 v108, 16, v4
	v_and_b32_e32 v109, 0xffff0000, v4
	v_lshlrev_b32_e32 v110, 16, v5
	v_and_b32_e32 v111, 0xffff0000, v5
	v_pk_fma_f32 v[46:47], v[46:47], v[80:81], v[96:97]
	v_pk_fma_f32 v[48:49], v[48:49], v[82:83], v[98:99]
	global_store_dwordx4 v[62:63], v[46:49], off
	v_pk_fma_f32 v[100:101], v[44:45], v[84:85], v[100:101]
	v_pk_fma_f32 v[102:103], v[42:43], v[86:87], v[102:103]
	global_store_dwordx4 v[62:63], v[100:103], off offset:1024
	v_pk_fma_f32 v[104:105], v[40:41], v[88:89], v[104:105]
	v_pk_fma_f32 v[106:107], v[38:39], v[90:91], v[106:107]
	global_store_dwordx4 v[62:63], v[104:107], off offset:2048
	v_pk_fma_f32 v[108:109], v[36:37], v[92:93], v[108:109]
	v_pk_fma_f32 v[110:111], v[34:35], v[94:95], v[110:111]
	global_store_dwordx4 v[62:63], v[108:111], off offset:3072
	s_waitcnt vmcnt(4)
	v_mov_b64_e32 v[24:25], v[26:27]
	v_mov_b64_e32 v[22:23], v[28:29]
	v_mov_b64_e32 v[18:19], v[30:31]
	v_mov_b64_e32 v[4:5], v[32:33]
	v_mov_b32_e32 v53, v0
	v_mov_b32_e32 v20, v52
	s_andn2_b64 exec, exec, s[10:11]
	s_cbranch_execz .LBB0_1393
.LBB0_1388:
	v_ashrrev_i32_e32 v21, 11, v20
	v_mul_i32_i24_e32 v54, 0x1800, v21
	v_ashrrev_i32_e32 v55, 31, v54
	v_lshl_add_u64 v[54:55], v[54:55], 2, s[84:85]
	v_lshl_add_u64 v[58:59], v[54:55], 0, s[12:13]
	v_lshl_add_u64 v[54:55], v[58:59], 0, v[8:9]
	global_load_dwordx4 v[80:83], v[54:55], off
	v_lshl_add_u64 v[54:55], v[58:59], 0, v[10:11]
	global_load_dwordx4 v[84:87], v[54:55], off
	v_lshl_add_u64 v[54:55], v[58:59], 0, v[12:13]
	global_load_dwordx4 v[88:91], v[54:55], off
	v_lshl_add_u64 v[54:55], v[58:59], 0, v[14:15]
	global_load_dwordx4 v[92:95], v[54:55], off
	v_add_u32_e32 v52, s33, v20
	v_cmp_gt_i32_e32 vcc, s17, v52
	v_cmp_lt_i32_e64 s[0:1], s16, v52
	s_and_b64 s[18:19], s[2:3], vcc
	v_mov_b32_e32 v0, -1
	s_and_saveexec_b64 s[14:15], s[18:19]
	s_cbranch_execz .LBB0_1390
	v_ashrrev_i32_e32 v0, 7, v52
	v_and_or_b32 v26, v0, -16, v50
	v_ashrrev_i32_e32 v27, 31, v26
	v_lshlrev_b64 v[26:27], 13, v[26:27]
	v_and_b32_e32 v0, 0x7ff, v52
	s_waitcnt lgkmcnt(0)
	v_lshl_add_u64 v[26:27], s[4:5], 0, v[26:27]
	v_lshlrev_b32_e32 v0, 2, v0
	v_lshl_add_u64 v[26:27], v[26:27], 0, v[0:1]
	global_load_dword v0, v[26:27], off
.LBB0_1390:
	s_or_b64 exec, exec, s[14:15]
	v_cndmask_b32_e32 v26, 0, v52, vcc
	v_ashrrev_i32_e32 v27, 31, v26
	v_lshlrev_b64 v[26:27], 11, v[26:27]
	v_lshl_add_u64 v[34:35], v[2:3], 0, v[26:27]
	global_load_dwordx2 v[26:27], v[34:35], off
	global_load_dwordx2 v[28:29], v[34:35], off offset:512
	global_load_dwordx2 v[30:31], v[34:35], off offset:1024
	global_load_dwordx2 v[32:33], v[34:35], off offset:1536
	v_ashrrev_i32_e32 v21, 11, v20
	s_waitcnt vmcnt(12)
	v_cmp_lt_i32_e32 vcc, -1, v53
	s_cbranch_vccz .LBB0_1386
	v_mov_b32_e32 v46, 0
	v_lshlrev_b32_e32 v54, 4, v21
	v_mov_b32_e32 v47, v46
	v_mov_b32_e32 v48, v46
	v_mov_b32_e32 v49, v46
	v_mov_b32_e32 v44, v46
	v_mov_b32_e32 v45, v46
	v_mov_b32_e32 v42, v46
	v_mov_b32_e32 v43, v46
	v_mov_b32_e32 v40, v46
	v_mov_b32_e32 v41, v46
	v_mov_b32_e32 v38, v46
	v_mov_b32_e32 v39, v46
	v_mov_b32_e32 v36, v46
	v_mov_b32_e32 v37, v46
	v_mov_b32_e32 v34, v46
	v_mov_b32_e32 v35, v46
